# phase-0 weight transposes: both tile loads issued together (second into fresh registers) with counted waits; tile-start barrier no longer drains the previous store
# speedup vs baseline: 1.0100x; 1.0100x over previous
.LBB0_949:
	s_andn2_b64 vcc, exec, s[0:1]
	s_cbranch_vccnz .LBB0_951
	s_add_i32 s0, s12, 0xfffff980
	s_lshr_b32 s54, s0, 7
	s_lshl_b64 s[0:1], s[54:55], 21
	s_add_u32 s2, s64, s0
	s_addc_u32 s3, s65, s1
	s_lshl_b64 s[0:1], s[54:55], 20
	v_readlane_b32 s6, v253, 1
	s_add_u32 s0, s6, s0
	v_readlane_b32 s6, v253, 2
	s_addc_u32 s1, s6, s1
	s_and_b32 s7, s10, 0x1c0
	v_mov_b32_e32 v8, v250
	s_and_b32 s6, s11, 0x3c0
	s_lshl_b32 s13, s7, 2
	v_lshlrev_b32_e32 v0, 4, v8
	v_ashrrev_i32_e32 v6, 4, v8
	s_add_u32 s2, s2, s13
	v_and_b32_e32 v176, 0xf0, v0
	v_add_u32_e32 v0, s6, v6
	s_addc_u32 s3, s3, 0
	v_ashrrev_i32_e32 v1, 31, v0
	v_lshl_add_u64 v[4:5], s[2:3], 0, v[176:177]
	v_lshlrev_b64 v[0:1], 11, v[0:1]
	v_lshl_add_u64 v[0:1], v[4:5], 0, v[0:1]
	s_waitcnt lgkmcnt(0)
	s_barrier
	global_load_dwordx4 v[0:3], v[0:1], off
	v_add_u32_e32 v12, 0x200, v8
	v_ashrrev_i32_e32 v10, 4, v12
	v_add_u32_e32 v12, s6, v10
	v_ashrrev_i32_e32 v13, 31, v12
	v_lshlrev_b64 v[12:13], 11, v[12:13]
	v_lshl_add_u64 v[12:13], v[4:5], 0, v[12:13]
	global_load_dwordx4 v[12:15], v[12:13], off
	s_movk_i32 s13, 0x104
	v_mad_u64_u32 v[6:7], s[2:3], v6, s13, v[176:177]
	v_ashrrev_i32_e32 v9, 3, v8
	s_lshl_b32 s54, s6, 1
	v_mad_u64_u32 v[4:5], s[2:3], v10, s13, v[176:177]
	s_waitcnt vmcnt(1)
	ds_write2_b32 v6, v0, v1 offset1:1
	ds_write2_b32 v6, v2, v3 offset0:2 offset1:3
	s_waitcnt vmcnt(0)
	ds_write2_b32 v4, v12, v13 offset1:1
	ds_write2_b32 v4, v14, v15 offset0:2 offset1:3
	v_lshlrev_b32_e32 v0, 3, v8
	v_and_b32_e32 v176, 56, v0
	v_mul_u32_u24_e32 v0, 0x104, v176
	v_lshl_add_u32 v4, v9, 2, v0
	s_waitcnt lgkmcnt(0)
	s_barrier
	ds_read2_b32 v[0:1], v4 offset1:65
	ds_read2_b32 v[2:3], v4 offset0:130 offset1:195
	v_add_u32_e32 v6, 0x400, v4
	ds_read2_b32 v[4:5], v6 offset0:4 offset1:69
	ds_read2_b32 v[6:7], v6 offset0:134 offset1:199
	s_waitcnt lgkmcnt(3)
	v_cvt_pk_bf16_f32 v0, v0, v1
	s_waitcnt lgkmcnt(2)
	v_cvt_pk_bf16_f32 v1, v2, v3
	s_waitcnt lgkmcnt(1)
	v_cvt_pk_bf16_f32 v2, v4, v5
	v_add_u32_e32 v4, s7, v9
	v_ashrrev_i32_e32 v5, 31, v4
	v_lshlrev_b64 v[4:5], 11, v[4:5]
	v_lshl_add_u64 v[4:5], s[0:1], 0, v[4:5]
	s_waitcnt lgkmcnt(0)
	v_cvt_pk_bf16_f32 v3, v6, v7
	v_lshl_add_u64 v[4:5], v[4:5], 0, s[54:55]

.LBB0_952:
	s_andn2_b64 vcc, exec, s[0:1]
	s_cbranch_vccnz .LBB0_954
	s_add_i32 s0, s12, 0xfffffb80
	s_lshr_b32 s54, s0, 8
	s_lshl_b64 s[0:1], s[54:55], 22
	s_add_u32 s2, s66, s0
	s_addc_u32 s3, s67, s1
	s_lshl_b64 s[0:1], s[54:55], 21
	s_add_u32 s0, s21, s0
	v_readlane_b32 s6, v253, 0
	s_addc_u32 s1, s6, s1
	s_and_b32 s7, s10, 0x3c0
	v_mov_b32_e32 v8, v250
	s_and_b32 s6, s9, 0x3c0
	s_lshl_b32 s13, s7, 2
	v_lshlrev_b32_e32 v0, 4, v8
	v_ashrrev_i32_e32 v6, 4, v8
	s_add_u32 s2, s2, s13
	v_and_b32_e32 v176, 0xf0, v0
	v_add_u32_e32 v0, s6, v6
	s_addc_u32 s3, s3, 0
	v_ashrrev_i32_e32 v1, 31, v0
	v_lshl_add_u64 v[4:5], s[2:3], 0, v[176:177]
	v_lshlrev_b64 v[0:1], 12, v[0:1]
	v_lshl_add_u64 v[0:1], v[4:5], 0, v[0:1]
	s_waitcnt lgkmcnt(0)
	s_barrier
	global_load_dwordx4 v[0:3], v[0:1], off
	v_add_u32_e32 v12, 0x200, v8
	v_ashrrev_i32_e32 v10, 4, v12
	v_add_u32_e32 v12, s6, v10
	v_ashrrev_i32_e32 v13, 31, v12
	v_lshlrev_b64 v[12:13], 12, v[12:13]
	v_lshl_add_u64 v[12:13], v[4:5], 0, v[12:13]
	global_load_dwordx4 v[12:15], v[12:13], off
	s_movk_i32 s13, 0x104
	v_mad_u64_u32 v[6:7], s[2:3], v6, s13, v[176:177]
	v_ashrrev_i32_e32 v9, 3, v8
	s_lshl_b32 s54, s6, 1
	v_mad_u64_u32 v[4:5], s[2:3], v10, s13, v[176:177]
	s_waitcnt vmcnt(1)
	ds_write2_b32 v6, v0, v1 offset1:1
	ds_write2_b32 v6, v2, v3 offset0:2 offset1:3
	s_waitcnt vmcnt(0)
	ds_write2_b32 v4, v12, v13 offset1:1
	ds_write2_b32 v4, v14, v15 offset0:2 offset1:3
	v_lshlrev_b32_e32 v0, 3, v8
	v_and_b32_e32 v176, 56, v0
	v_mul_u32_u24_e32 v0, 0x104, v176
	v_lshl_add_u32 v4, v9, 2, v0
	s_waitcnt lgkmcnt(0)
	s_barrier
	ds_read2_b32 v[0:1], v4 offset1:65
	ds_read2_b32 v[2:3], v4 offset0:130 offset1:195
	v_add_u32_e32 v6, 0x400, v4
	ds_read2_b32 v[4:5], v6 offset0:4 offset1:69
	ds_read2_b32 v[6:7], v6 offset0:134 offset1:199
	s_waitcnt lgkmcnt(3)
	v_cvt_pk_bf16_f32 v0, v0, v1
	s_waitcnt lgkmcnt(2)
	v_cvt_pk_bf16_f32 v1, v2, v3
	s_waitcnt lgkmcnt(1)
	v_cvt_pk_bf16_f32 v2, v4, v5
	v_add_u32_e32 v4, s7, v9
	v_ashrrev_i32_e32 v5, 31, v4
	v_lshlrev_b64 v[4:5], 11, v[4:5]
	v_lshl_add_u64 v[4:5], s[0:1], 0, v[4:5]
	s_waitcnt lgkmcnt(0)
	v_cvt_pk_bf16_f32 v3, v6, v7
	v_lshl_add_u64 v[4:5], v[4:5], 0, s[54:55]

.LBB0_955:
	s_andn2_b64 vcc, exec, s[0:1]
	s_cbranch_vccnz .LBB0_944
	s_mul_hi_i32 s0, s12, 0x38e38e39
	s_lshr_b32 s1, s0, 31
	s_ashr_i32 s0, s0, 7
	s_add_i32 s0, s0, s1
	s_mul_i32 s1, s0, 0xfffffdc0
	s_add_i32 s1, s12, s1
	s_mul_i32 s2, s1, 0xe39
	s_lshr_b32 s3, s2, 31
	s_ashr_i32 s2, s2, 17
	s_add_i32 s6, s2, s3
	s_mul_i32 s2, s6, 36
	s_sub_i32 s1, s1, s2
	s_mul_i32 s3, s0, 0x900000
	s_mul_hi_i32 s2, s0, 0x900000
	s_waitcnt lgkmcnt(0)
	s_add_u32 s13, s84, s3
	s_addc_u32 s18, s85, s2
	s_mul_hi_i32 s3, s0, 0x480000
	s_mul_i32 s0, s0, 0x480000
	s_sext_i32_i16 s1, s1
	s_add_u32 s2, s53, s0
	s_addc_u32 s3, s97, s3
	s_lshl_b32 s0, s6, 6
	s_lshl_b32 s6, s1, 6
	s_ashr_i32 s7, s6, 31
	v_mov_b32_e32 v8, v250
	s_lshl_b64 s[14:15], s[6:7], 2
	s_add_u32 s14, s13, s14
	v_lshlrev_b32_e32 v0, 4, v8
	s_addc_u32 s15, s18, s15
	v_and_b32_e32 v176, 0xf0, v0
	v_ashrrev_i32_e32 v6, 4, v8
	v_lshl_add_u64 v[4:5], s[14:15], 0, v[176:177]
	v_add_u32_e32 v0, s0, v6
	s_movk_i32 s7, 0x2400
	v_mad_i64_i32 v[0:1], s[14:15], v0, s7, v[4:5]
	s_nop 0
	s_barrier
	global_load_dwordx4 v[0:3], v[0:1], off
	v_add_u32_e32 v12, 0x200, v8
	v_ashrrev_i32_e32 v10, 4, v12
	v_add_u32_e32 v12, s0, v10
	v_mad_i64_i32 v[12:13], s[14:15], v12, s7, v[4:5]
	global_load_dwordx4 v[12:15], v[12:13], off
	s_movk_i32 s1, 0x104
	v_mad_u64_u32 v[6:7], s[14:15], v6, s1, v[176:177]
	v_ashrrev_i32_e32 v9, 3, v8
	v_mad_u64_u32 v[4:5], s[14:15], v10, s1, v[176:177]
	s_ashr_i32 s1, s0, 31
	s_waitcnt vmcnt(1)
	ds_write2_b32 v6, v0, v1 offset1:1
	ds_write2_b32 v6, v2, v3 offset0:2 offset1:3
	s_waitcnt vmcnt(0)
	ds_write2_b32 v4, v12, v13 offset1:1
	ds_write2_b32 v4, v14, v15 offset0:2 offset1:3
	v_lshlrev_b32_e32 v0, 3, v8
	v_and_b32_e32 v176, 56, v0
	v_mul_u32_u24_e32 v0, 0x104, v176
	v_lshl_add_u32 v4, v9, 2, v0
	s_waitcnt lgkmcnt(0)
	s_barrier
	ds_read2_b32 v[0:1], v4 offset1:65
	ds_read2_b32 v[2:3], v4 offset0:130 offset1:195
	v_add_u32_e32 v6, 0x400, v4
	ds_read2_b32 v[4:5], v6 offset0:4 offset1:69
	ds_read2_b32 v[6:7], v6 offset0:134 offset1:199
	s_waitcnt lgkmcnt(3)
	v_cvt_pk_bf16_f32 v0, v0, v1
	s_waitcnt lgkmcnt(2)
	v_cvt_pk_bf16_f32 v1, v2, v3
	s_waitcnt lgkmcnt(1)
	v_cvt_pk_bf16_f32 v2, v4, v5
	v_add_u32_e32 v4, s6, v9
	v_ashrrev_i32_e32 v5, 31, v4
	v_lshlrev_b64 v[4:5], 11, v[4:5]
	v_lshl_add_u64 v[4:5], s[2:3], 0, v[4:5]
	s_waitcnt lgkmcnt(0)
	v_cvt_pk_bf16_f32 v3, v6, v7
	v_lshl_add_u64 v[4:5], s[0:1], 1, v[4:5]
	s_branch .LBB0_944
